# v9 plus the same next-tile-load reorder (after the first K-fragment LDS reads) in the MOBA and SLC loops
# speedup vs baseline: 1.0060x; 1.0010x over previous
; #define LAS __attribute__((address_space(3)))
; #define FA_SBAR() __builtin_amdgcn_sched_barrier(0)
; #define QK_MM(F0, F1, g) do { _Pragma("unroll") for (int e = 0; e < 2; ++e) { const int d0 = 2 * (g) + e; \
;         p0 = __builtin_amdgcn_mfma_f32_32x32x16_f16(F0[e], qr[d0], p0, 0, 0, 0); p1 = __builtin_amdgcn_mfma_f32_32x32x16_f16(F1[e], qr[d0], p1, 0, 0, 0); } } while (0)
; __device__ __forceinline__ void mask_all(f32x16& p0, f32x16& p1, bool keep) {
;     const float NEG = -__builtin_inff();
; #pragma unroll
;     for (int r = 0; r < 16; ++r) { p0[r] = keep ? p0[r] : NEG; p1[r] = keep ? p1[r] : NEG; }
; }
; template <bool MLA>
; __device__ __forceinline__ void qkt2(f32x16& p0, f32x16& p1, const LAS char* lds, int kboff, int kroff, int r32, int hi, const half8* qr) {
;     const LAS char* kb[4];
; #pragma unroll
;     for (int dd = 0; dd < 4; ++dd) kb[dd] = lds + OFF_K + kboff + FA_KSWZ(r32, (dd * 16 + hi * 8) * 2);
;     constexpr int NG = MLA ? 6 : 4;
;     half8 fa0[2], fa1[2], fb0[2], fb1[2];
;     ...
; #pragma unroll
;     for (int r = 0; r < 16; ++r) { p0[r] = 0.f; p1[r] = 0.f; }
;     QK_LD(fa0, fa1, 0); FA_SBAR();
;     QK_LD(fb0, fb1, 1); FA_SBAR(); QK_MM(fa0, fa1, 0); FA_SBAR();
;     QK_LD(fa0, fa1, 2); FA_SBAR(); QK_MM(fb0, fb1, 1); FA_SBAR();
;     QK_LD(fb0, fb1, 3); FA_SBAR(); QK_MM(fa0, fa1, 2); FA_SBAR();
;     if constexpr (NG == 6) {
;         QK_LD(fa0, fa1, 4); FA_SBAR(); QK_MM(fb0, fb1, 3); FA_SBAR();
;         QK_LD(fb0, fb1, 5); FA_SBAR(); QK_MM(fa0, fa1, 4); FA_SBAR();
;         QK_MM(fb0, fb1, 5);
;     } else QK_MM(fb0, fb1, 3);
;     ...
; }
.LBB0_4950:
	s_sub_i32 s8, s22, 63
	s_and_b32 s9, s23, 1
	v_mov_b32_e32 v2, s9
	s_cmp_gt_i32 s8, s24
	s_cbranch_scc1 .Lmoba_skipq
	v_lshlrev_b32_e32 v2, 14, v2
	v_add_u32_e32 v4, v229, v2
	v_add_u32_e32 v16, v4, v230
	v_add_u32_e32 v17, v4, v231
	v_add_u32_e32 v102, v4, v232
	v_add_u32_e32 v103, v4, v233
	ds_read_b128 v[4:7], v16 offset:32768
	ds_read_b128 v[8:11], v16 offset:40960
	ds_read_b128 v[12:15], v17 offset:32768
	ds_read_b128 v[82:85], v17 offset:40960
	ds_read_b128 v[86:89], v102 offset:32768
	ds_read_b128 v[90:93], v102 offset:40960
	ds_read_b128 v[94:97], v103 offset:32768
	ds_read_b128 v[98:101], v103 offset:40960
	s_and_b64 vcc, exec, s[6:7]
	s_cbranch_vccz .Lmoba_q_nold
	v_add_u32_e32 v114, s22, v204
	v_add_u32_e32 v116, 1, v114
	v_ashrrev_i32_e32 v117, 31, v116
	v_add_u32_e32 v120, 33, v114
	v_lshlrev_b64 v[116:117], 8, v[116:117]
	v_ashrrev_i32_e32 v121, 31, v120
	v_lshl_add_u64 v[118:119], v[206:207], 0, v[116:117]
	v_lshlrev_b64 v[120:121], 8, v[120:121]
	v_lshl_add_u64 v[116:117], v[208:209], 0, v[116:117]
	v_lshl_add_u64 v[122:123], v[206:207], 0, v[120:121]
	global_load_dwordx4 v[146:149], v[118:119], off
	global_load_dwordx4 v[150:153], v[122:123], off
	v_lshl_add_u64 v[118:119], v[208:209], 0, v[120:121]
	global_load_dwordx4 v[154:157], v[116:117], off
	global_load_dwordx4 v[158:161], v[118:119], off
.Lmoba_q_nold:
	s_waitcnt lgkmcnt(7)
	v_mfma_f32_32x32x16_f16 v[114:129], v[4:7], v[162:165], 0
	s_waitcnt lgkmcnt(6)
	v_mfma_f32_32x32x16_f16 v[130:145], v[8:11], v[162:165], 0
	s_waitcnt lgkmcnt(5)
	v_mfma_f32_32x32x16_f16 v[114:129], v[12:15], v[166:169], v[114:129]
	s_waitcnt lgkmcnt(4)
	v_mfma_f32_32x32x16_f16 v[130:145], v[82:85], v[166:169], v[130:145]
	ds_read_b128 v[4:7], v16 offset:32896
	ds_read_b128 v[8:11], v16 offset:41088
	ds_read_b128 v[12:15], v17 offset:32896
	ds_read_b128 v[82:85], v17 offset:41088
	s_waitcnt lgkmcnt(7)
	v_mfma_f32_32x32x16_f16 v[114:129], v[86:89], v[170:173], v[114:129]
	s_waitcnt lgkmcnt(6)
	v_mfma_f32_32x32x16_f16 v[130:145], v[90:93], v[170:173], v[130:145]
	s_waitcnt lgkmcnt(5)
	v_mfma_f32_32x32x16_f16 v[114:129], v[94:97], v[174:177], v[114:129]
	s_waitcnt lgkmcnt(4)
	v_mfma_f32_32x32x16_f16 v[130:145], v[98:101], v[174:177], v[130:145]
	ds_read_b128 v[86:89], v102 offset:32896
	ds_read_b128 v[90:93], v102 offset:41088
	ds_read_b128 v[94:97], v103 offset:32896
	ds_read_b128 v[98:101], v103 offset:41088
	s_waitcnt lgkmcnt(7)
	v_mfma_f32_32x32x16_f16 v[114:129], v[4:7], v[178:181], v[114:129]
	s_waitcnt lgkmcnt(6)
	v_mfma_f32_32x32x16_f16 v[130:145], v[8:11], v[178:181], v[130:145]
	s_waitcnt lgkmcnt(5)
	v_mfma_f32_32x32x16_f16 v[114:129], v[12:15], v[182:185], v[114:129]
	s_waitcnt lgkmcnt(4)
	v_mfma_f32_32x32x16_f16 v[130:145], v[82:85], v[182:185], v[130:145]
	s_waitcnt lgkmcnt(3)
	v_mfma_f32_32x32x16_f16 v[114:129], v[86:89], v[186:189], v[114:129]
	s_lshr_b32 s38, s23, 2
	s_mov_b64 s[8:9], -1
	s_cmp_lg_u32 s38, s25
	s_waitcnt lgkmcnt(2)
	v_mfma_f32_32x32x16_f16 v[130:145], v[90:93], v[186:189], v[130:145]
	s_waitcnt lgkmcnt(1)
	v_mfma_f32_32x32x16_f16 v[114:129], v[94:97], v[190:193], v[114:129]
	s_waitcnt lgkmcnt(0)
	v_mfma_f32_32x32x16_f16 v[130:145], v[98:101], v[190:193], v[130:145]
	s_cbranch_scc0 .LBB0_4953
	v_bfe_u32 v4, v227, s38, 1
	v_cmp_eq_u32_e32 vcc, 0, v4
	s_mov_b64 s[8:9], 0
	s_nop 5
	v_cndmask_b32_e32 v98, v114, v218, vcc
	s_nop 0
	v_cndmask_b32_e32 v82, v130, v218, vcc
	v_cndmask_b32_e32 v99, v115, v218, vcc
	v_cndmask_b32_e32 v83, v131, v218, vcc
	v_cndmask_b32_e32 v100, v116, v218, vcc
	v_cndmask_b32_e32 v84, v132, v218, vcc
	v_cndmask_b32_e32 v101, v117, v218, vcc
	v_cndmask_b32_e32 v85, v133, v218, vcc
	v_cndmask_b32_e32 v102, v118, v218, vcc
	v_cndmask_b32_e32 v86, v134, v218, vcc
	v_cndmask_b32_e32 v103, v119, v218, vcc
	v_cndmask_b32_e32 v87, v135, v218, vcc
	v_cndmask_b32_e32 v104, v120, v218, vcc
	v_cndmask_b32_e32 v88, v136, v218, vcc
	v_cndmask_b32_e32 v105, v121, v218, vcc
	v_cndmask_b32_e32 v89, v137, v218, vcc
	v_cndmask_b32_e32 v106, v122, v218, vcc
	v_cndmask_b32_e32 v90, v138, v218, vcc
	v_cndmask_b32_e32 v107, v123, v218, vcc
	v_cndmask_b32_e32 v91, v139, v218, vcc
	v_cndmask_b32_e32 v108, v124, v218, vcc
	v_cndmask_b32_e32 v92, v140, v218, vcc
	v_cndmask_b32_e32 v109, v125, v218, vcc
	v_cndmask_b32_e32 v93, v141, v218, vcc
	v_cndmask_b32_e32 v110, v126, v218, vcc
	v_cndmask_b32_e32 v94, v142, v218, vcc
	v_cndmask_b32_e32 v111, v127, v218, vcc
	v_cndmask_b32_e32 v95, v143, v218, vcc
	v_cndmask_b32_e32 v112, v128, v218, vcc
	v_cndmask_b32_e32 v96, v144, v218, vcc
	v_cndmask_b32_e32 v113, v129, v218, vcc
	v_cndmask_b32_e32 v97, v145, v218, vcc

; template <int KIND>
; __device__ __forceinline__ void run_unit(LAS char* lds, const UnitArgs& U, int tid_in) {
;     ...
;     for (int t = 0; t < NT; ++t) {
;         if (t + 1 < NT) FA_LOADT(U.j_lo + t + 1);
.Lmoba_skipq:
	s_and_b64 vcc, exec, s[6:7]
	s_cbranch_vccz .LBB0_4962
	v_add_u32_e32 v2, s22, v204
	v_add_u32_e32 v4, 1, v2
	v_ashrrev_i32_e32 v5, 31, v4
	v_add_u32_e32 v8, 33, v2
	v_lshlrev_b64 v[4:5], 8, v[4:5]
	v_ashrrev_i32_e32 v9, 31, v8
	v_lshl_add_u64 v[6:7], v[206:207], 0, v[4:5]
	v_lshlrev_b64 v[8:9], 8, v[8:9]
	v_lshl_add_u64 v[4:5], v[208:209], 0, v[4:5]
	v_lshl_add_u64 v[10:11], v[206:207], 0, v[8:9]
	global_load_dwordx4 v[146:149], v[6:7], off
	global_load_dwordx4 v[150:153], v[10:11], off
	v_lshl_add_u64 v[6:7], v[208:209], 0, v[8:9]
	global_load_dwordx4 v[154:157], v[4:5], off
	global_load_dwordx4 v[158:161], v[6:7], off
	s_branch .LBB0_4962

; #define LAS __attribute__((address_space(3)))
; #define FA_SBAR() __builtin_amdgcn_sched_barrier(0)
; #define QK_MM(F0, F1, g) do { _Pragma("unroll") for (int e = 0; e < 2; ++e) { const int d0 = 2 * (g) + e; \
;         p0 = __builtin_amdgcn_mfma_f32_32x32x16_f16(F0[e], qr[d0], p0, 0, 0, 0); p1 = __builtin_amdgcn_mfma_f32_32x32x16_f16(F1[e], qr[d0], p1, 0, 0, 0); } } while (0)
; template <bool MLA>
; __device__ __forceinline__ void qkt2(f32x16& p0, f32x16& p1, const LAS char* lds, int kboff, int kroff, int r32, int hi, const half8* qr) {
;     const LAS char* kb[4];
; #pragma unroll
;     for (int dd = 0; dd < 4; ++dd) kb[dd] = lds + OFF_K + kboff + FA_KSWZ(r32, (dd * 16 + hi * 8) * 2);
;     constexpr int NG = MLA ? 6 : 4;
;     half8 fa0[2], fa1[2], fb0[2], fb1[2];
;     ...
; #pragma unroll
;     for (int r = 0; r < 16; ++r) { p0[r] = 0.f; p1[r] = 0.f; }
;     QK_LD(fa0, fa1, 0); FA_SBAR();
;     QK_LD(fb0, fb1, 1); FA_SBAR(); QK_MM(fa0, fa1, 0); FA_SBAR();
.LBB0_4992:
	s_sub_i32 s10, s22, 63
	s_and_b32 s11, s25, 1
	v_mov_b32_e32 v2, s11
	s_cmp_gt_i32 s10, s24
	s_cbranch_scc1 .Lslc_skipq
	v_lshlrev_b32_e32 v2, 14, v2
	v_add_u32_e32 v4, v182, v2
	v_add_u32_e32 v16, v4, v183
	v_add_u32_e32 v17, v4, v184
	v_add_u32_e32 v191, v4, v185
	v_add_u32_e32 v196, v4, v186
	ds_read_b128 v[4:7], v16 offset:32768
	ds_read_b128 v[8:11], v16 offset:40960
	ds_read_b128 v[12:15], v17 offset:32768
	ds_read_b128 v[192:195], v17 offset:40960
	ds_read_b128 v[204:207], v191 offset:32768
	ds_read_b128 v[220:223], v191 offset:40960
	ds_read_b128 v[224:227], v196 offset:32768
	ds_read_b128 v[228:231], v196 offset:40960
	s_and_b64 vcc, exec, s[6:7]
	s_cbranch_vccz .Lslc_q_nold
	v_add_u32_e32 v98, s22, v166
	v_add_u32_e32 v100, 1, v98
	v_ashrrev_i32_e32 v101, 31, v100
	v_add_u32_e32 v104, 33, v98
	v_lshlrev_b64 v[100:101], 8, v[100:101]
	v_ashrrev_i32_e32 v105, 31, v104
	v_lshl_add_u64 v[102:103], v[170:171], 0, v[100:101]
	v_lshlrev_b64 v[104:105], 8, v[104:105]
	v_lshl_add_u64 v[100:101], v[172:173], 0, v[100:101]
	v_lshl_add_u64 v[106:107], v[170:171], 0, v[104:105]
	global_load_dwordx4 v[114:117], v[102:103], off
	global_load_dwordx4 v[118:121], v[106:107], off
	v_lshl_add_u64 v[102:103], v[172:173], 0, v[104:105]
	global_load_dwordx4 v[122:125], v[100:101], off
	global_load_dwordx4 v[126:129], v[102:103], off
; #define FA_SBAR() __builtin_amdgcn_sched_barrier(0)
; #define QK_MM(F0, F1, g) do { _Pragma("unroll") for (int e = 0; e < 2; ++e) { const int d0 = 2 * (g) + e; \
;         p0 = __builtin_amdgcn_mfma_f32_32x32x16_f16(F0[e], qr[d0], p0, 0, 0, 0); p1 = __builtin_amdgcn_mfma_f32_32x32x16_f16(F1[e], qr[d0], p1, 0, 0, 0); } } while (0)
; template <bool MLA>
; __device__ __forceinline__ void qkt2(f32x16& p0, f32x16& p1, const LAS char* lds, int kboff, int kroff, int r32, int hi, const half8* qr) {
;     ...
; #pragma unroll
;     for (int r = 0; r < 16; ++r) { p0[r] = 0.f; p1[r] = 0.f; }
;     QK_LD(fa0, fa1, 0); FA_SBAR();
;     QK_LD(fb0, fb1, 1); FA_SBAR(); QK_MM(fa0, fa1, 0); FA_SBAR();
;     QK_LD(fa0, fa1, 2); FA_SBAR(); QK_MM(fb0, fb1, 1); FA_SBAR();
;     QK_LD(fb0, fb1, 3); FA_SBAR(); QK_MM(fa0, fa1, 2); FA_SBAR();
;     if constexpr (NG == 6) {
;         QK_LD(fa0, fa1, 4); FA_SBAR(); QK_MM(fb0, fb1, 3); FA_SBAR();
;         QK_LD(fb0, fb1, 5); FA_SBAR(); QK_MM(fa0, fa1, 4); FA_SBAR();
;         QK_MM(fb0, fb1, 5);
;     } else QK_MM(fb0, fb1, 3);
;     ...
; }
.Lslc_q_nold:
	s_waitcnt lgkmcnt(7)
	v_mfma_f32_32x32x16_f16 v[98:113], v[4:7], v[134:137], 0
	s_waitcnt lgkmcnt(6)
	v_mfma_f32_32x32x16_f16 v[82:97], v[8:11], v[134:137], 0
	s_waitcnt lgkmcnt(5)
	v_mfma_f32_32x32x16_f16 v[98:113], v[12:15], v[138:141], v[98:113]
	s_waitcnt lgkmcnt(4)
	v_mfma_f32_32x32x16_f16 v[82:97], v[192:195], v[138:141], v[82:97]
	ds_read_b128 v[4:7], v16 offset:32896
	ds_read_b128 v[8:11], v16 offset:41088
	ds_read_b128 v[12:15], v17 offset:32896
	ds_read_b128 v[192:195], v17 offset:41088
	s_waitcnt lgkmcnt(7)
	v_mfma_f32_32x32x16_f16 v[98:113], v[204:207], v[142:145], v[98:113]
	s_waitcnt lgkmcnt(6)
	v_mfma_f32_32x32x16_f16 v[82:97], v[220:223], v[142:145], v[82:97]
	s_waitcnt lgkmcnt(5)
	v_mfma_f32_32x32x16_f16 v[98:113], v[224:227], v[146:149], v[98:113]
	s_waitcnt lgkmcnt(4)
	v_mfma_f32_32x32x16_f16 v[82:97], v[228:231], v[146:149], v[82:97]
	ds_read_b128 v[204:207], v191 offset:32896
	ds_read_b128 v[220:223], v191 offset:41088
	ds_read_b128 v[224:227], v196 offset:32896
	ds_read_b128 v[228:231], v196 offset:41088
	s_waitcnt lgkmcnt(7)
	v_mfma_f32_32x32x16_f16 v[98:113], v[4:7], v[150:153], v[98:113]
	s_waitcnt lgkmcnt(6)
	v_mfma_f32_32x32x16_f16 v[82:97], v[8:11], v[150:153], v[82:97]
	s_waitcnt lgkmcnt(5)
	v_mfma_f32_32x32x16_f16 v[98:113], v[12:15], v[154:157], v[98:113]
	s_waitcnt lgkmcnt(4)
	v_mfma_f32_32x32x16_f16 v[82:97], v[192:195], v[154:157], v[82:97]
	s_waitcnt lgkmcnt(3)
	v_mfma_f32_32x32x16_f16 v[98:113], v[204:207], v[158:161], v[98:113]
	s_cmp_lt_u32 s25, 32
	s_cselect_b64 vcc, -1, 0
	s_cmp_lt_u32 s25, 64
	s_cselect_b64 s[38:39], -1, 0
	s_cmpk_lt_u32 s25, 0x60
	s_cselect_b64 s[40:41], -1, 0
	v_cndmask_b32_e64 v4, v133, v132, s[40:41]
	s_waitcnt lgkmcnt(2)
	v_mfma_f32_32x32x16_f16 v[82:97], v[220:223], v[158:161], v[82:97]
	v_cndmask_b32_e64 v4, v4, v131, s[38:39]
	v_cndmask_b32_e32 v4, v4, v130, vcc
	s_and_b32 s10, s25, 31
	v_bfe_u32 v4, v4, s10, 1
	v_cmp_eq_u32_e32 vcc, 0, v4
	s_cmp_le_i32 s22, s23
	s_waitcnt lgkmcnt(1)
	v_mfma_f32_32x32x16_f16 v[98:113], v[224:227], v[162:165], v[98:113]
	s_waitcnt lgkmcnt(0)
	v_mfma_f32_32x32x16_f16 v[82:97], v[228:231], v[162:165], v[82:97]
	s_nop 9
	v_cndmask_b32_e32 v193, v98, v218, vcc
	v_cndmask_b32_e32 v204, v99, v218, vcc
	v_cndmask_b32_e32 v191, v100, v218, vcc
	v_cndmask_b32_e32 v192, v101, v218, vcc
	v_cndmask_b32_e32 v101, v102, v218, vcc
	v_cndmask_b32_e32 v102, v103, v218, vcc
	v_cndmask_b32_e32 v99, v104, v218, vcc
	v_cndmask_b32_e32 v82, v82, v218, vcc
	v_cndmask_b32_e32 v83, v83, v218, vcc
	v_cndmask_b32_e32 v16, v84, v218, vcc
	v_cndmask_b32_e32 v17, v85, v218, vcc
	v_cndmask_b32_e32 v14, v86, v218, vcc
	v_cndmask_b32_e32 v15, v87, v218, vcc
	v_cndmask_b32_e32 v12, v88, v218, vcc
	v_cndmask_b32_e32 v100, v105, v218, vcc
	v_cndmask_b32_e32 v13, v89, v218, vcc
	v_cndmask_b32_e32 v98, v106, v218, vcc
	v_cndmask_b32_e32 v10, v90, v218, vcc
	v_cndmask_b32_e32 v90, v107, v218, vcc
	v_cndmask_b32_e32 v11, v91, v218, vcc
	v_cndmask_b32_e32 v88, v108, v218, vcc
	v_cndmask_b32_e32 v8, v92, v218, vcc
	v_cndmask_b32_e32 v89, v109, v218, vcc
	v_cndmask_b32_e32 v9, v93, v218, vcc
	v_cndmask_b32_e32 v86, v110, v218, vcc
	v_cndmask_b32_e32 v6, v94, v218, vcc
	v_cndmask_b32_e32 v87, v111, v218, vcc
	v_cndmask_b32_e32 v7, v95, v218, vcc
	v_cndmask_b32_e32 v84, v112, v218, vcc
	v_cndmask_b32_e32 v4, v96, v218, vcc
	v_cndmask_b32_e32 v85, v113, v218, vcc
	v_cndmask_b32_e32 v5, v97, v218, vcc
	s_cbranch_scc1 .LBB0_4995
	v_add_u32_e32 v91, 59, v188
	v_cmp_gt_u32_e32 vcc, 2.0, v91
	v_add_u32_e32 v91, 27, v188
	s_nop 0
	v_cndmask_b32_e32 v193, v218, v193, vcc
	v_cmp_gt_u32_e32 vcc, 2.0, v91
	v_add_u32_e32 v91, 58, v188
	s_nop 0
	v_cndmask_b32_e32 v82, v218, v82, vcc
	v_cmp_gt_u32_e32 vcc, 2.0, v91
	v_add_u32_e32 v91, 26, v188
	s_nop 0
	v_cndmask_b32_e32 v204, v218, v204, vcc
	v_cmp_gt_u32_e32 vcc, 2.0, v91
	v_add_u32_e32 v91, 57, v188
	s_nop 0
	v_cndmask_b32_e32 v83, v218, v83, vcc
	v_cmp_gt_u32_e32 vcc, 2.0, v91
	v_add_u32_e32 v91, 25, v188
	s_nop 0
	v_cndmask_b32_e32 v191, v218, v191, vcc
	v_cmp_gt_u32_e32 vcc, 2.0, v91
	v_add_u32_e32 v91, 56, v188
	s_nop 0
	v_cndmask_b32_e32 v16, v218, v16, vcc
	v_cmp_gt_u32_e32 vcc, 2.0, v91
	v_add_u32_e32 v91, 24, v188
	s_nop 0
	v_cndmask_b32_e32 v192, v218, v192, vcc
	v_cmp_gt_u32_e32 vcc, 2.0, v91
	v_add_u32_e32 v91, 51, v188
	s_nop 0
	v_cndmask_b32_e32 v17, v218, v17, vcc
	v_cmp_gt_u32_e32 vcc, 2.0, v91
	v_add_u32_e32 v91, 19, v188
	s_nop 0
	v_cndmask_b32_e32 v101, v218, v101, vcc
	v_cmp_gt_u32_e32 vcc, 2.0, v91
	v_add_u32_e32 v91, 50, v188
	s_nop 0
	v_cndmask_b32_e32 v14, v218, v14, vcc
	v_cmp_gt_u32_e32 vcc, 2.0, v91
	v_add_u32_e32 v91, 18, v188
	s_nop 0
	v_cndmask_b32_e32 v102, v218, v102, vcc
	v_cmp_gt_u32_e32 vcc, 2.0, v91
	v_add_u32_e32 v91, 49, v188
	s_nop 0
	v_cndmask_b32_e32 v15, v218, v15, vcc
	v_cmp_gt_u32_e32 vcc, 2.0, v91
	v_add_u32_e32 v91, 17, v188
	s_nop 0
	v_cndmask_b32_e32 v99, v218, v99, vcc
	v_cmp_gt_u32_e32 vcc, 2.0, v91
	v_add_u32_e32 v91, 48, v188
	s_nop 0
	v_cndmask_b32_e32 v12, v218, v12, vcc
	v_cmp_gt_u32_e32 vcc, 2.0, v91
	v_add_u32_e32 v91, 16, v188
	s_nop 0
	v_cndmask_b32_e32 v100, v218, v100, vcc
	v_cmp_gt_u32_e32 vcc, 2.0, v91
	v_add_u32_e32 v91, 43, v188
	s_nop 0
	v_cndmask_b32_e32 v13, v218, v13, vcc
	v_cmp_gt_u32_e32 vcc, 2.0, v91
	v_add_u32_e32 v91, 11, v188
	s_nop 0
	v_cndmask_b32_e32 v98, v218, v98, vcc
	v_cmp_gt_u32_e32 vcc, 2.0, v91
	v_add_u32_e32 v91, 42, v188
	s_nop 0
	v_cndmask_b32_e32 v10, v218, v10, vcc
	v_cmp_gt_u32_e32 vcc, 2.0, v91
	v_add_u32_e32 v91, 10, v188
	s_nop 0
	v_cndmask_b32_e32 v90, v218, v90, vcc
	v_cmp_gt_u32_e32 vcc, 2.0, v91
	v_add_u32_e32 v91, 41, v188
	s_nop 0
	v_cndmask_b32_e32 v11, v218, v11, vcc
	v_cmp_gt_u32_e32 vcc, 2.0, v91
	v_add_u32_e32 v91, 9, v188
	s_nop 0
	v_cndmask_b32_e32 v88, v218, v88, vcc
	v_cmp_gt_u32_e32 vcc, 2.0, v91
	v_add_u32_e32 v91, 40, v188
	s_nop 0
	v_cndmask_b32_e32 v8, v218, v8, vcc
	v_cmp_gt_u32_e32 vcc, 2.0, v91
	v_add_u32_e32 v91, 8, v188
	s_nop 0
	v_cndmask_b32_e32 v89, v218, v89, vcc
	v_cmp_gt_u32_e32 vcc, 2.0, v91
	v_add_u32_e32 v91, 35, v188
	s_nop 0
	v_cndmask_b32_e32 v9, v218, v9, vcc
	v_cmp_gt_u32_e32 vcc, 2.0, v91
	v_add_u32_e32 v91, 3, v188
	s_nop 0
	v_cndmask_b32_e32 v86, v218, v86, vcc
	v_cmp_gt_u32_e32 vcc, 2.0, v91
	v_add_u32_e32 v91, 34, v188
	s_nop 0
	v_cndmask_b32_e32 v6, v218, v6, vcc
	v_cmp_gt_u32_e32 vcc, 2.0, v91
	v_add_u32_e32 v91, 2, v188
	s_nop 0
	v_cndmask_b32_e32 v87, v218, v87, vcc
	v_cmp_gt_u32_e32 vcc, 2.0, v91
	v_add_u32_e32 v91, 33, v188
	s_nop 0
	v_cndmask_b32_e32 v7, v218, v7, vcc
	v_cmp_gt_u32_e32 vcc, 2.0, v91
	v_add_u32_e32 v91, 1, v188
	s_nop 0
	v_cndmask_b32_e32 v84, v218, v84, vcc
	v_cmp_gt_u32_e32 vcc, 2.0, v91
	v_add_u32_e32 v91, 32, v188
	s_nop 0
	v_cndmask_b32_e32 v4, v218, v4, vcc
	v_cmp_gt_u32_e32 vcc, 2.0, v91
	s_nop 1
	v_cndmask_b32_e32 v85, v218, v85, vcc
	v_cmp_gt_u32_e32 vcc, 2.0, v188
	s_nop 1
	v_cndmask_b32_e32 v5, v218, v5, vcc

; template <int KIND>
; __device__ __forceinline__ void run_unit(LAS char* lds, const UnitArgs& U, int tid_in) {
;     ...
;     for (int t = 0; t < NT; ++t) {
;         if (t + 1 < NT) FA_LOADT(U.j_lo + t + 1);
.Lslc_skipq:
	s_and_b64 vcc, exec, s[6:7]
	s_cbranch_vccz .LBB0_5000
	v_add_u32_e32 v2, s22, v166
	v_add_u32_e32 v4, 1, v2
	v_ashrrev_i32_e32 v5, 31, v4
	v_add_u32_e32 v8, 33, v2
	v_lshlrev_b64 v[4:5], 8, v[4:5]
	v_ashrrev_i32_e32 v9, 31, v8
	v_lshl_add_u64 v[6:7], v[170:171], 0, v[4:5]
	v_lshlrev_b64 v[8:9], 8, v[8:9]
	v_lshl_add_u64 v[4:5], v[172:173], 0, v[4:5]
	v_lshl_add_u64 v[10:11], v[170:171], 0, v[8:9]
	global_load_dwordx4 v[114:117], v[6:7], off
	global_load_dwordx4 v[118:121], v[10:11], off
	v_lshl_add_u64 v[6:7], v[172:173], 0, v[8:9]
	global_load_dwordx4 v[122:125], v[4:5], off
	global_load_dwordx4 v[126:129], v[6:7], off
	s_branch .LBB0_5000
